# in-projection pass-1|pass-2 grid barrier: workgroups that still own a pass-2 tile only ARRIVE (no wait for the release) and acquire the release just before their first mixer-preparation item
# speedup vs baseline: 1.0264x; 1.0032x over previous
_Z10hybrid_fwd6Params:
	s_mov_b32 s100, 2
	s_nop 0
	v_writelane_b32 v255, s100, 21
	s_mov_b32 s100, 0
	s_nop 0
	v_writelane_b32 v255, s100, 23
	s_load_dwordx2 s[42:43], s[0:1], 0xb8
	s_mov_b64 s[78:79], s[0:1]
	s_add_u32 s0, s78, 0xb8
	s_addc_u32 s1, s79, 0
	v_and_b32_e32 v1, 0x3ff, v0
	s_waitcnt lgkmcnt(0)
	s_and_b32 s3, s42, 7
	v_readfirstlane_b32 s38, v1
	s_cmp_lg_u32 s3, 0
	s_mov_b32 s41, s2
	s_cbranch_scc1 .LBB0_2
	s_ashr_i32 s4, s2, 31
	s_lshr_b32 s4, s4, 29
	s_add_i32 s4, s2, s4
	s_and_b32 s5, s4, -8
	s_ashr_i32 s3, s42, 3
	s_sub_i32 s5, s2, s5
	s_mul_i32 s3, s3, s5
	s_ashr_i32 s4, s4, 3
	s_add_i32 s41, s3, s4

.Lgb258_local:
	s_cmp_lt_u32 s2, 0x98
	s_cbranch_scc0 .Lgb258_lw
	s_mov_b32 s14, 1
	s_nop 0
	v_writelane_b32 v255, s14, 23
	v_writelane_b32 v255, s7, 22
	s_branch .Lgb258_done

.Lp1_defer_wait:
	v_readlane_b32 s6, v252, 7
	v_readlane_b32 s7, v252, 8
	s_mov_b64 s[4:5], 0
	s_nop 0
	s_and_b64 vcc, exec, s[6:7]
	s_cbranch_vccnz .Lp1_dw_nl
	v_mbcnt_lo_u32_b32 v0, -1, 0
	v_mbcnt_hi_u32_b32 v0, -1, v0
	s_nop 0
	v_cmp_eq_u32_e32 vcc, 0, v0
	s_and_b64 s[4:5], vcc, exec
.Lp1_dw_nl:
	s_and_saveexec_b64 s[40:41], s[4:5]
	s_cbranch_execz .Lp1_dw_end
	v_readlane_b32 s8, v255, 23
	s_nop 0
	s_cmp_eq_u32 s8, 1
	s_cbranch_scc0 .Lp1_dw_end
	s_mov_b32 s8, 0
	s_nop 0
	v_writelane_b32 v255, s8, 23
	v_readlane_b32 s7, v255, 22
	s_getreg_b32 s6, hwreg(HW_REG_XCC_ID, 0, 4)
	s_and_b32 s6, s6, 15
	s_lshl_b32 s6, s6, 8
	s_add_u32 s14, s6, 0x6400
	v_mov_b32_e32 v3, s14
	s_mov_b32 s16, 0x10000
	global_load_dword v6, v3, s[46:47] sc1
	s_sleep 4
	global_load_dword v7, v3, s[46:47] sc1
	s_sleep 4
	global_load_dword v8, v3, s[46:47] sc1
	s_sleep 4

.Lp1_dw_end:
	s_or_b64 exec, exec, s[40:41]
	s_waitcnt lgkmcnt(0)
	s_barrier
